# final_row_ss of batch b-1 moved from phase j=14 into the in-proj tail of batch b, run by the workgroups that own one in-proj unit fewer (bx>=128)
# speedup vs baseline: 1.0065x; 1.0065x over previous
.LBB0_564:
	s_mov_b32 s0, -1
	s_nop 0
	v_mbcnt_lo_u32_b32 v0, s0, 0
	v_mbcnt_hi_u32_b32 v0, s0, v0
	v_readlane_b32 s0, v250, 25
	s_nop 1
	v_add_u32_e32 v0, s0, v0
	v_readlane_b32 s0, v250, 38
	v_readlane_b32 s1, v250, 39
	v_and_b32_e32 v10, 63, v0
	s_andn2_b64 vcc, exec, s[0:1]
	v_lshlrev_b32_e32 v2, 4, v10
	s_cmp_gt_i32 s92, 22
	s_cbranch_scc0 .LBB0_567
	s_cbranch_vccnz .LBB0_567
	v_readlane_b32 s0, v254, 22
	s_add_u32 s0, s0, s86
	v_readlane_b32 s1, v254, 23
	v_mov_b32_e32 v3, v64
	v_readlane_b32 s36, v250, 1
	s_addc_u32 s1, s1, s87
	v_readlane_b32 s42, v250, 7
	v_readlane_b32 s43, v250, 8
	v_lshl_add_u64 v[4:5], s[0:1], 0, v[2:3]
	v_readlane_b32 s0, v254, 29
	s_waitcnt lgkmcnt(0)
	v_lshl_add_u64 v[0:1], s[42:43], 0, v[2:3]
	v_readlane_b32 s1, v254, 30
	v_readlane_b32 s2, v254, 55
	v_readlane_b32 s37, v250, 2
	v_readlane_b32 s38, v250, 3
	v_readlane_b32 s39, v250, 4
	v_readlane_b32 s40, v250, 5
	v_readlane_b32 s41, v250, 6
	v_readlane_b32 s3, v254, 56
	global_load_dwordx4 v[40:43], v[0:1], off
	global_load_dwordx4 v[44:47], v[0:1], off offset:1024
	global_load_dwordx4 v[48:51], v[0:1], off offset:2048
	global_load_dwordx4 v[52:55], v[0:1], off offset:3072

.LBB0_916:
	s_waitcnt vmcnt(0)
	v_readlane_b32 s50, v255, 28
	v_readlane_b32 s70, v255, 26
	v_readlane_b32 s51, v255, 29
	v_readlane_b32 s48, v255, 30
	v_readlane_b32 s74, v255, 32
	v_readlane_b32 s42, v255, 35
	v_readlane_b32 s71, v255, 27
	v_readlane_b32 s49, v255, 31
	v_readlane_b32 s75, v255, 33
	v_readlane_b32 s51, v255, 34
	v_readlane_b32 s43, v255, 36
	s_movk_i32 s78, 0xf800
	s_barrier
	s_cmp_lt_i32 s92, 12
	s_cbranch_scc1 .Lfr_skip
	v_readlane_b32 s0, v250, 0
	s_nop 3
	s_cmp_lt_u32 s0, 0x80
	s_cbranch_scc1 .Lfr_skip
	v_mbcnt_lo_u32_b32 v0, -1, 0
	v_mbcnt_hi_u32_b32 v0, -1, v0
	v_lshlrev_b32_e32 v2, 4, v0
	v_mov_b32_e32 v3, v64
	v_readlane_b32 s98, v250, 7
	v_readlane_b32 s99, v250, 8
	s_nop 4
	global_load_dwordx4 v[40:43], v2, s[98:99]
	global_load_dwordx4 v[44:47], v2, s[98:99] offset:1024
	global_load_dwordx4 v[48:51], v2, s[98:99] offset:2048
	global_load_dwordx4 v[52:55], v2, s[98:99] offset:3072
	v_readlane_b32 s98, v254, 22
	v_readlane_b32 s99, v254, 23
	s_mov_b32 s3, 0xffc00000
	s_cmp_gt_i32 s92, 22
	s_cselect_b32 s3, 0x3c00000, s3
	s_ashr_i32 s100, s3, 31
	s_add_u32 s98, s98, s3
	s_addc_u32 s99, s99, s100
	v_lshl_add_u64 v[4:5], s[98:99], 0, v[2:3]
	v_readlane_b32 s0, v254, 29
	v_readlane_b32 s1, v254, 30
	v_readlane_b32 s2, v254, 55
	s_nop 1
	s_sub_u32 s0, s0, 0x10000
	s_subb_u32 s1, s1, 0
	s_sub_i32 s2, s2, 0x400
	s_mov_b32 s100, 0x400000
	s_mov_b32 s101, 0
.Lfr_loop:
	global_load_dwordx4 v[24:27], v64, s[0:1] offset:-48
	global_load_dwordx4 v[28:31], v64, s[0:1] offset:-32
	global_load_dwordx4 v[32:35], v64, s[0:1] offset:-16
	global_load_dwordx4 v[36:39], v64, s[0:1]
	global_load_dwordx4 v[6:9], v[4:5], off offset:-2048
	global_load_dwordx4 v[12:15], v[4:5], off offset:-1024
	global_load_dwordx4 v[16:19], v[4:5], off
	global_load_dwordx4 v[20:23], v[4:5], off offset:1024
	s_add_i32 s2, s2, 0x400
	s_add_u32 s0, s0, 0x10000
	s_addc_u32 s1, s1, 0
	s_waitcnt vmcnt(4)
	v_add_f32_e32 v24, v24, v25
	v_add_f32_e32 v26, v26, v27
	v_add_f32_e32 v28, v28, v29
	v_add_f32_e32 v30, v30, v31
	v_add_f32_e32 v32, v32, v33
	v_add_f32_e32 v34, v34, v35
	v_add_f32_e32 v36, v36, v37
	v_add_f32_e32 v38, v38, v39
	v_add_f32_e32 v24, v24, v26
	v_add_f32_e32 v28, v28, v30
	v_add_f32_e32 v32, v32, v34
	v_add_f32_e32 v36, v36, v38
	v_add_f32_e32 v24, v24, v28
	v_add_f32_e32 v24, v24, v32
	v_add_f32_e32 v24, v24, v36
	v_fmamk_f32 v24, v24, 0x3a800000, v176
	v_rsq_f32_e32 v24, v24
	s_waitcnt vmcnt(0)
	v_pk_mul_f32 v[6:7], v[6:7], v[24:25] op_sel_hi:[1,0]
	v_pk_mul_f32 v[8:9], v[8:9], v[24:25] op_sel_hi:[1,0]
	v_pk_mul_f32 v[12:13], v[12:13], v[24:25] op_sel_hi:[1,0]
	v_pk_mul_f32 v[14:15], v[14:15], v[24:25] op_sel_hi:[1,0]
	v_pk_mul_f32 v[16:17], v[16:17], v[24:25] op_sel_hi:[1,0]
	v_pk_mul_f32 v[18:19], v[18:19], v[24:25] op_sel_hi:[1,0]
	v_pk_mul_f32 v[20:21], v[20:21], v[24:25] op_sel_hi:[1,0]
	v_pk_mul_f32 v[22:23], v[22:23], v[24:25] op_sel_hi:[1,0]
	v_pk_mul_f32 v[6:7], v[6:7], v[40:41]
	v_pk_mul_f32 v[8:9], v[8:9], v[42:43]
	v_pk_mul_f32 v[12:13], v[12:13], v[44:45]
	v_pk_mul_f32 v[14:15], v[14:15], v[46:47]
	v_pk_mul_f32 v[16:17], v[16:17], v[48:49]
	v_pk_mul_f32 v[18:19], v[18:19], v[50:51]
	v_pk_mul_f32 v[20:21], v[20:21], v[52:53]
	v_pk_mul_f32 v[22:23], v[22:23], v[54:55]
	global_store_dwordx4 v[4:5], v[6:9], off offset:-2048
	global_store_dwordx4 v[4:5], v[12:15], off offset:-1024
	global_store_dwordx4 v[4:5], v[16:19], off
	global_store_dwordx4 v[4:5], v[20:23], off offset:1024
	v_lshl_add_u64 v[4:5], v[4:5], 0, s[100:101]
	s_cmpk_gt_i32 s2, 0x3fff
	s_cbranch_scc0 .Lfr_loop
.Lfr_skip:
.LBB0_917:
	s_andn2_b64 vcc, exec, s[84:85]
	s_mov_b32 s2, s79
	s_mov_b32 s3, s82
	s_cbranch_vccnz .LBB0_1064
	v_readlane_b32 s2, v254, 10
	v_readlane_b32 s3, v254, 11
	v_readfirstlane_b32 s8, v188
	s_andn2_b64 vcc, exec, s[2:3]
	v_cndmask_b32_e64 v0, 0, 1, s[2:3]
	v_cmp_ne_u32_e64 s[0:1], 1, v0
	s_cbranch_vccnz .LBB0_920
	v_readlane_b32 s2, v254, 15
	s_mov_b32 s38, s2
	v_readlane_b32 s2, v254, 14
	s_mov_b32 s40, s2
